# final LayerNorm visits the most recently written row blocks first (sweep order permuted to follow the MLP2 tile schedule) so more of H is still in the memory-side cache
# speedup vs baseline: 1.0189x; 1.0035x over previous
.LBB0_835:
	v_mov_b32_e32 v58, 0
	v_mov_b32_e32 v59, 0
	s_cmp_lg_u32 s20, 0x800
	s_cbranch_scc1 .Lfl_noperm
	v_lshrrev_b32_e32 v58, 11, v32
	v_and_b32_e32 v59, 3, v58
	v_lshrrev_b32_e32 v60, 2, v58
	v_sub_u32_e32 v60, 3, v60
	v_lshl_or_b32 v59, v59, 2, v60
	v_sub_u32_e32 v58, v59, v58
	v_ashrrev_i32_e32 v59, 31, v58
	v_lshlrev_b64 v[58:59], 23, v[58:59]
.Lfl_noperm:
	v_lshl_add_u64 v[56:57], v[50:51], 0, v[168:169]
	v_lshl_add_u64 v[56:57], v[56:57], 0, v[58:59]
	v_lshl_add_u64 v[54:55], v[52:53], 0, v[168:169]
	v_lshl_add_u64 v[54:55], v[54:55], 0, v[58:59]
	global_load_dwordx4 v[24:27], v[56:57], off
	global_load_dwordx4 v[28:31], v[54:55], off
	global_load_dwordx4 v[16:19], v[56:57], off offset:1024
	global_load_dwordx4 v[20:23], v[54:55], off offset:1024
	global_load_dwordx4 v[8:11], v[56:57], off offset:2048
	global_load_dwordx4 v[12:15], v[54:55], off offset:2048
	global_load_dwordx4 v[0:3], v[56:57], off offset:3072
	global_load_dwordx4 v[4:7], v[54:55], off offset:3072
	v_readlane_b32 s0, v252, 12
	v_readlane_b32 s1, v252, 13
	s_andn2_b64 vcc, exec, s[0:1]
	s_waitcnt vmcnt(0)
	v_mov_b32_e32 v58, v25
	v_mov_b32_e32 v59, v26
	v_mov_b32_e32 v60, v24
	v_mov_b32_e32 v61, v27
	v_pk_add_f32 v[58:59], v[58:59], v[60:61]
	v_mov_b32_e32 v60, v29
	v_mov_b32_e32 v61, v30
	v_mov_b32_e32 v62, v28
	v_mov_b32_e32 v63, v31
	v_pk_add_f32 v[60:61], v[60:61], v[62:63]
	v_mov_b32_e32 v62, v17
	v_mov_b32_e32 v63, v18
	v_mov_b32_e32 v64, v16
	v_mov_b32_e32 v65, v19
	v_pk_add_f32 v[62:63], v[62:63], v[64:65]
	v_add_f32_e32 v33, v58, v59
	v_pk_add_f32 v[62:63], v[62:63], v[62:63] op_sel:[0,1] op_sel_hi:[1,0]
	v_mov_b32_e32 v64, v21
	v_mov_b32_e32 v65, v22
	v_mov_b32_e32 v66, v20
	v_mov_b32_e32 v67, v23
	v_add_f32_e32 v58, 0, v33
	v_pk_add_f32 v[64:65], v[64:65], v[66:67]
	v_add_f32_e32 v66, v8, v9
	s_waitcnt lgkmcnt(1)
	v_add_f32_e32 v68, v10, v11
	v_mov_b32_e32 v59, v0
	v_mov_b32_e32 v63, v1
	v_mov_b32_e32 v67, v2
	s_waitcnt lgkmcnt(0)
	v_mov_b32_e32 v69, v3
	v_add_f32_e32 v33, v60, v61
	v_pk_add_f32 v[64:65], v[64:65], v[64:65] op_sel:[0,1] op_sel_hi:[1,0]
	v_pk_add_f32 v[58:59], v[58:59], v[62:63]
	v_pk_add_f32 v[62:63], v[66:67], v[68:69]
	v_add_f32_e32 v60, 0, v33
	v_add_f32_e32 v76, v12, v13
	v_add_f32_e32 v78, v14, v15
	v_pk_add_f32 v[58:59], v[58:59], v[62:63]
	v_mov_b32_e32 v61, v4
	v_mov_b32_e32 v65, v5
	v_mov_b32_e32 v77, v6
	v_mov_b32_e32 v79, v7
	v_add_f32_e32 v33, v58, v59
	v_pk_add_f32 v[58:59], v[60:61], v[64:65]
	v_pk_add_f32 v[60:61], v[76:77], v[78:79]
	s_nop 0
	v_pk_add_f32 v[58:59], v[58:59], v[60:61]
	s_nop 0
	v_add_f32_e32 v58, v58, v59
	ds_bpermute_b32 v59, v70, v33
	s_waitcnt lgkmcnt(0)
	v_add_f32_e32 v33, v33, v59
	ds_bpermute_b32 v59, v70, v58
	s_waitcnt lgkmcnt(0)
	v_add_f32_e32 v58, v58, v59
	ds_bpermute_b32 v59, v71, v33
	s_waitcnt lgkmcnt(0)
	v_add_f32_e32 v33, v33, v59
	ds_bpermute_b32 v59, v71, v58
	s_waitcnt lgkmcnt(0)
	v_add_f32_e32 v58, v58, v59
	ds_bpermute_b32 v59, v72, v33
	s_waitcnt lgkmcnt(0)
	v_add_f32_e32 v33, v33, v59
	ds_bpermute_b32 v59, v72, v58
	s_waitcnt lgkmcnt(0)
	v_add_f32_e32 v58, v58, v59
	ds_bpermute_b32 v59, v73, v33
	s_waitcnt lgkmcnt(0)
	v_add_f32_e32 v33, v33, v59
	ds_bpermute_b32 v59, v73, v58
	s_waitcnt lgkmcnt(0)
	v_add_f32_e32 v58, v58, v59
	ds_bpermute_b32 v59, v74, v33
	s_waitcnt lgkmcnt(0)
	v_add_f32_e32 v33, v33, v59
	ds_bpermute_b32 v59, v74, v58
	s_waitcnt lgkmcnt(0)
	v_add_f32_e32 v58, v58, v59
	ds_bpermute_b32 v59, v75, v33
	s_waitcnt lgkmcnt(0)
	v_add_f32_e32 v33, v33, v59
	ds_bpermute_b32 v59, v75, v58
	v_fmamk_f32 v26, v33, 0xba800000, v26
	v_fmamk_f32 v27, v33, 0xba800000, v27
	v_mov_b32_e32 v64, v26
	v_fmac_f32_e32 v24, 0xba800000, v33
	s_waitcnt lgkmcnt(0)
	v_add_f32_e32 v80, v58, v59
	v_fmamk_f32 v61, v80, 0xba800000, v31
	v_fmamk_f32 v58, v33, 0xba800000, v25
	v_fmamk_f32 v60, v80, 0xba800000, v30
	v_fmamk_f32 v59, v80, 0xba800000, v29
	v_fmac_f32_e32 v28, 0xba800000, v80
	v_mov_b32_e32 v65, v61
	v_mov_b32_e32 v25, v28
	v_pk_mul_f32 v[30:31], v[58:59], v[58:59]
	v_pk_mov_b32 v[62:63], v[26:27], v[60:61] op_sel:[1,0]
	v_pk_mul_f32 v[64:65], v[64:65], v[64:65]
	v_pk_fma_f32 v[30:31], v[24:25], v[24:25], v[30:31]
	v_pk_fma_f32 v[62:63], v[62:63], v[62:63], v[64:65]
	v_fmamk_f32 v18, v33, 0xba800000, v18
	v_fmamk_f32 v23, v80, 0xba800000, v23
	v_pk_add_f32 v[66:67], v[30:31], v[62:63]
	v_fmamk_f32 v19, v33, 0xba800000, v19
	v_fmamk_f32 v30, v33, 0xba800000, v17
	v_fmamk_f32 v22, v80, 0xba800000, v22
	v_fmamk_f32 v31, v80, 0xba800000, v21
	v_fmac_f32_e32 v20, 0xba800000, v80
	v_mov_b32_e32 v68, v18
	v_mov_b32_e32 v69, v23
	v_fmac_f32_e32 v16, 0xba800000, v33
	v_mov_b32_e32 v17, v20
	v_pk_mul_f32 v[62:63], v[30:31], v[30:31]
	v_pk_mov_b32 v[64:65], v[18:19], v[22:23] op_sel:[1,0]
	v_pk_mul_f32 v[68:69], v[68:69], v[68:69]
	v_pk_fma_f32 v[62:63], v[16:17], v[16:17], v[62:63]
	v_pk_fma_f32 v[64:65], v[64:65], v[64:65], v[68:69]
	v_fmamk_f32 v10, v33, 0xba800000, v10
	v_pk_add_f32 v[68:69], v[62:63], v[64:65]
	v_fmamk_f32 v62, v33, 0xba800000, v9
	v_fmamk_f32 v15, v80, 0xba800000, v15
	v_fmamk_f32 v63, v80, 0xba800000, v13
	v_fmac_f32_e32 v12, 0xba800000, v80
	v_fmamk_f32 v11, v33, 0xba800000, v11
	v_fmac_f32_e32 v8, 0xba800000, v33
	v_fmamk_f32 v14, v80, 0xba800000, v14
	v_mov_b32_e32 v9, v12
	v_pk_mul_f32 v[64:65], v[62:63], v[62:63]
	v_mov_b32_e32 v78, v10
	v_mov_b32_e32 v79, v15
	v_pk_fma_f32 v[76:77], v[8:9], v[8:9], v[64:65]
	v_pk_mov_b32 v[64:65], v[10:11], v[14:15] op_sel:[1,0]
	v_pk_mul_f32 v[78:79], v[78:79], v[78:79]
	v_fmamk_f32 v2, v33, 0xba800000, v2
	v_fmamk_f32 v7, v80, 0xba800000, v7
	v_pk_fma_f32 v[78:79], v[64:65], v[64:65], v[78:79]
	v_fmamk_f32 v3, v33, 0xba800000, v3
	v_fmamk_f32 v64, v33, 0xba800000, v1
	v_fmamk_f32 v6, v80, 0xba800000, v6
	v_fmamk_f32 v65, v80, 0xba800000, v5
	v_fmac_f32_e32 v4, 0xba800000, v80
	v_mov_b32_e32 v84, v2
	v_mov_b32_e32 v85, v7
	v_fmac_f32_e32 v0, 0xba800000, v33
	v_mov_b32_e32 v1, v4
	v_pk_mul_f32 v[80:81], v[64:65], v[64:65]
	v_pk_mov_b32 v[82:83], v[2:3], v[6:7] op_sel:[1,0]
	v_pk_mul_f32 v[84:85], v[84:85], v[84:85]
	v_pk_add_f32 v[66:67], v[66:67], v[68:69]
	v_pk_add_f32 v[68:69], v[76:77], v[78:79]
	v_pk_fma_f32 v[76:77], v[82:83], v[82:83], v[84:85]
	v_pk_add_f32 v[66:67], v[68:69], v[66:67]
	v_pk_fma_f32 v[68:69], v[0:1], v[0:1], v[80:81]
	s_nop 0
	v_pk_add_f32 v[68:69], v[68:69], v[76:77]
	s_nop 0
	v_pk_add_f32 v[66:67], v[68:69], v[66:67]
	ds_bpermute_b32 v68, v70, v66
	ds_bpermute_b32 v69, v70, v67
	s_waitcnt lgkmcnt(0)
	v_pk_add_f32 v[66:67], v[66:67], v[68:69]
	ds_bpermute_b32 v68, v71, v66
	ds_bpermute_b32 v69, v71, v67
	s_waitcnt lgkmcnt(0)
	v_pk_add_f32 v[66:67], v[66:67], v[68:69]
	ds_bpermute_b32 v68, v72, v66
	ds_bpermute_b32 v69, v72, v67
	s_waitcnt lgkmcnt(0)
	v_pk_add_f32 v[66:67], v[66:67], v[68:69]
	ds_bpermute_b32 v68, v73, v66
	ds_bpermute_b32 v69, v73, v67
	s_waitcnt lgkmcnt(0)
	v_pk_add_f32 v[66:67], v[66:67], v[68:69]
	ds_bpermute_b32 v68, v74, v66
	ds_bpermute_b32 v69, v74, v67
	s_waitcnt lgkmcnt(0)
	v_pk_add_f32 v[66:67], v[66:67], v[68:69]
	ds_bpermute_b32 v68, v75, v66
	ds_bpermute_b32 v69, v75, v67
	s_cbranch_vccnz .LBB0_834
	v_mov_b32_e32 v17, v30
	v_mov_b32_e32 v21, v31
	s_waitcnt lgkmcnt(0)
	v_pk_add_f32 v[30:31], v[66:67], v[68:69]
	s_mov_b32 s0, 0x3a800000
	v_pk_fma_f32 v[30:31], v[30:31], s[0:1], v[180:181] op_sel_hi:[1,0,0]
	s_mov_b32 s0, 0x800000
	v_mul_f32_e32 v33, 0x4b800000, v31
	v_cmp_gt_f32_e32 vcc, s0, v30
	v_cmp_gt_f32_e64 s[0:1], s0, v31
	v_mov_b32_e32 v25, v58
	v_mov_b32_e32 v9, v62
	v_cndmask_b32_e64 v31, v31, v33, s[0:1]
	v_rsq_f32_e32 v31, v31
	v_mov_b32_e32 v13, v63
	v_mov_b32_e32 v1, v64
	v_mov_b32_e32 v5, v65
	v_mul_f32_e32 v33, 0x45800000, v31
	v_cndmask_b32_e64 v58, v31, v33, s[0:1]
	v_pk_mul_f32 v[68:69], v[60:61], v[58:59] op_sel_hi:[1,0]
	global_load_dwordx4 v[60:63], v[34:35], off
	global_load_dwordx4 v[64:67], v[36:37], off
	v_mul_f32_e32 v31, 0x4b800000, v30
	v_cndmask_b32_e32 v30, v30, v31, vcc
	v_rsq_f32_e32 v30, v30
	v_mov_b32_e32 v29, v59
	v_pk_mul_f32 v[28:29], v[28:29], v[58:59] op_sel_hi:[1,0]
	v_mul_f32_e32 v31, 0x45800000, v30
	v_cndmask_b32_e32 v30, v30, v31, vcc
	v_pk_mul_f32 v[24:25], v[24:25], v[30:31] op_sel_hi:[1,0]
	v_pk_mul_f32 v[26:27], v[26:27], v[30:31] op_sel_hi:[1,0]
	v_pk_mul_f32 v[18:19], v[18:19], v[30:31] op_sel_hi:[1,0]
	v_pk_mul_f32 v[16:17], v[16:17], v[30:31] op_sel_hi:[1,0]
	v_pk_mul_f32 v[10:11], v[10:11], v[30:31] op_sel_hi:[1,0]
	v_pk_mul_f32 v[8:9], v[8:9], v[30:31] op_sel_hi:[1,0]
	v_pk_mul_f32 v[2:3], v[2:3], v[30:31] op_sel_hi:[1,0]
	v_pk_mul_f32 v[0:1], v[0:1], v[30:31] op_sel_hi:[1,0]
	s_waitcnt vmcnt(0)
	v_pk_fma_f32 v[26:27], v[26:27], v[62:63], v[66:67]
	v_pk_fma_f32 v[24:25], v[24:25], v[60:61], v[64:65]
	v_pk_fma_f32 v[78:79], v[68:69], v[62:63], v[66:67]
	v_pk_fma_f32 v[76:77], v[28:29], v[60:61], v[64:65]
	global_store_dwordx4 v[56:57], v[24:27], off
	global_store_dwordx4 v[54:55], v[76:79], off
	v_pk_mul_f32 v[28:29], v[22:23], v[58:59] op_sel_hi:[1,0]
	v_pk_mul_f32 v[60:61], v[20:21], v[58:59] op_sel_hi:[1,0]
	global_load_dwordx4 v[20:23], v[38:39], off
	global_load_dwordx4 v[24:27], v[40:41], off
	s_waitcnt vmcnt(0)
	v_pk_fma_f32 v[16:17], v[16:17], v[20:21], v[24:25]
	v_pk_fma_f32 v[18:19], v[18:19], v[22:23], v[26:27]
	v_pk_fma_f32 v[60:61], v[60:61], v[20:21], v[24:25]
	v_pk_fma_f32 v[62:63], v[28:29], v[22:23], v[26:27]
	global_store_dwordx4 v[56:57], v[16:19], off offset:1024
	global_store_dwordx4 v[54:55], v[60:63], off offset:1024
	v_pk_mul_f32 v[22:23], v[14:15], v[58:59] op_sel_hi:[1,0]
	v_pk_mul_f32 v[20:21], v[12:13], v[58:59] op_sel_hi:[1,0]
	global_load_dwordx4 v[12:15], v[42:43], off
	global_load_dwordx4 v[16:19], v[44:45], off
	s_waitcnt vmcnt(0)
	v_pk_fma_f32 v[8:9], v[8:9], v[12:13], v[16:17]
	v_pk_fma_f32 v[10:11], v[10:11], v[14:15], v[18:19]
	v_pk_fma_f32 v[20:21], v[20:21], v[12:13], v[16:17]
	v_pk_fma_f32 v[22:23], v[22:23], v[14:15], v[18:19]
	global_store_dwordx4 v[56:57], v[8:11], off offset:2048
	global_store_dwordx4 v[54:55], v[20:23], off offset:2048
	v_pk_mul_f32 v[14:15], v[6:7], v[58:59] op_sel_hi:[1,0]
	v_pk_mul_f32 v[12:13], v[4:5], v[58:59] op_sel_hi:[1,0]
	global_load_dwordx4 v[4:7], v[46:47], off
	global_load_dwordx4 v[8:11], v[48:49], off
	s_waitcnt vmcnt(0)
	v_pk_fma_f32 v[0:1], v[0:1], v[4:5], v[8:9]
	v_pk_fma_f32 v[2:3], v[2:3], v[6:7], v[10:11]
	v_pk_fma_f32 v[12:13], v[12:13], v[4:5], v[8:9]
	v_pk_fma_f32 v[14:15], v[14:15], v[6:7], v[10:11]
	global_store_dwordx4 v[56:57], v[0:3], off offset:3072
	global_store_dwordx4 v[54:55], v[12:15], off offset:3072
	s_branch .LBB0_834
